# adds: PEER value pass row gathers software-pipelined one token ahead (dedicated row buffer, idx prefetched two tokens ahead, counted waits), w_out epilogue residual loads batched, LayerNorm(mid) param
# speedup vs baseline: 1.0535x; 1.0153x over previous
.LBB0_860:
	global_load_dwordx4 v[192:195], v[8:9], off
	global_load_dwordx4 v[196:199], v[8:9], off offset:16
	v_ashrrev_i32_e32 v201, 31, v12
	v_mov_b32_e32 v200, v12
	v_lshlrev_b64 v[200:201], 11, v[200:201]
	v_lshl_add_u64 v[202:203], v[10:11], 0, v[200:201]
	global_load_dwordx4 v[218:221], v[202:203], off
	v_add_u32_e32 v200, 8, v12
	v_ashrrev_i32_e32 v201, 31, v200
	v_lshlrev_b64 v[200:201], 11, v[200:201]
	v_lshl_add_u64 v[204:205], v[10:11], 0, v[200:201]
	global_load_dwordx4 v[222:225], v[204:205], off
	v_add_u32_e32 v200, 16, v12
	v_ashrrev_i32_e32 v201, 31, v200
	v_lshlrev_b64 v[200:201], 11, v[200:201]
	v_lshl_add_u64 v[206:207], v[10:11], 0, v[200:201]
	global_load_dwordx4 v[226:229], v[206:207], off
	v_add_u32_e32 v200, 24, v12
	v_ashrrev_i32_e32 v201, 31, v200
	v_lshlrev_b64 v[200:201], 11, v[200:201]
	v_lshl_add_u64 v[208:209], v[10:11], 0, v[200:201]
	global_load_dwordx4 v[230:233], v[208:209], off
	v_add_u32_e32 v200, 32, v12
	v_ashrrev_i32_e32 v201, 31, v200
	v_lshlrev_b64 v[200:201], 11, v[200:201]
	v_lshl_add_u64 v[210:211], v[10:11], 0, v[200:201]
	global_load_dwordx4 v[234:237], v[210:211], off
	v_add_u32_e32 v200, 40, v12
	v_ashrrev_i32_e32 v201, 31, v200
	v_lshlrev_b64 v[200:201], 11, v[200:201]
	v_lshl_add_u64 v[212:213], v[10:11], 0, v[200:201]
	global_load_dwordx4 v[238:241], v[212:213], off
	v_add_u32_e32 v200, 48, v12
	v_ashrrev_i32_e32 v201, 31, v200
	v_lshlrev_b64 v[200:201], 11, v[200:201]
	v_lshl_add_u64 v[214:215], v[10:11], 0, v[200:201]
	global_load_dwordx4 v[242:245], v[214:215], off
	v_add_u32_e32 v200, 56, v12
	v_ashrrev_i32_e32 v201, 31, v200
	v_lshlrev_b64 v[200:201], 11, v[200:201]
	v_lshl_add_u64 v[216:217], v[10:11], 0, v[200:201]
	global_load_dwordx4 v[246:249], v[216:217], off
	s_waitcnt vmcnt(8)
	v_pk_add_f32 v[192:193], v[192:193], 1.0 op_sel_hi:[1,0]
	v_pk_add_f32 v[194:195], v[194:195], 1.0 op_sel_hi:[1,0]
	v_pk_add_f32 v[196:197], v[196:197], 1.0 op_sel_hi:[1,0]
	v_pk_add_f32 v[198:199], v[198:199], 1.0 op_sel_hi:[1,0]
	ds_read_b128 v[0:3], v14
	ds_read_b128 v[4:7], v14 offset:16
	s_waitcnt vmcnt(7)
	v_lshlrev_b32_e32 v16, 16, v218
	v_and_b32_e32 v17, 0xffff0000, v218
	v_lshlrev_b32_e32 v18, 16, v219
	v_and_b32_e32 v19, 0xffff0000, v219
	v_lshlrev_b32_e32 v20, 16, v220
	v_and_b32_e32 v21, 0xffff0000, v220
	v_lshlrev_b32_e32 v22, 16, v221
	v_and_b32_e32 v23, 0xffff0000, v221
	s_waitcnt lgkmcnt(0)
	v_pk_mul_f32 v[0:1], v[0:1], v[192:193]
	v_pk_mul_f32 v[2:3], v[2:3], v[194:195]
	v_pk_mul_f32 v[4:5], v[4:5], v[196:197]
	v_pk_mul_f32 v[6:7], v[6:7], v[198:199]
	v_pk_fma_f32 v[0:1], v[16:17], s[0:1], v[0:1] op_sel_hi:[1,0,1]
	v_pk_fma_f32 v[2:3], v[18:19], s[0:1], v[2:3] op_sel_hi:[1,0,1]
	v_pk_fma_f32 v[4:5], v[20:21], s[0:1], v[4:5] op_sel_hi:[1,0,1]
	v_pk_fma_f32 v[6:7], v[22:23], s[0:1], v[6:7] op_sel_hi:[1,0,1]
	s_nop 0
	v_cvt_pk_bf16_f32 v24, v0, v1
	v_cvt_pk_bf16_f32 v25, v2, v3
	v_cvt_pk_bf16_f32 v26, v4, v5
	v_cvt_pk_bf16_f32 v27, v6, v7
	global_store_dwordx4 v[202:203], v[24:27], off
	s_nop 1
	ds_read_b128 v[0:3], v14 offset:2176
	ds_read_b128 v[4:7], v14 offset:2192
	s_waitcnt vmcnt(7)
	v_lshlrev_b32_e32 v16, 16, v222
	v_and_b32_e32 v17, 0xffff0000, v222
	v_lshlrev_b32_e32 v18, 16, v223
	v_and_b32_e32 v19, 0xffff0000, v223
	v_lshlrev_b32_e32 v20, 16, v224
	v_and_b32_e32 v21, 0xffff0000, v224
	v_lshlrev_b32_e32 v22, 16, v225
	v_and_b32_e32 v23, 0xffff0000, v225
	s_waitcnt lgkmcnt(0)
	v_pk_mul_f32 v[0:1], v[0:1], v[192:193]
	v_pk_mul_f32 v[2:3], v[2:3], v[194:195]
	v_pk_mul_f32 v[4:5], v[4:5], v[196:197]
	v_pk_mul_f32 v[6:7], v[6:7], v[198:199]
	v_pk_fma_f32 v[0:1], v[16:17], s[0:1], v[0:1] op_sel_hi:[1,0,1]
	v_pk_fma_f32 v[2:3], v[18:19], s[0:1], v[2:3] op_sel_hi:[1,0,1]
	v_pk_fma_f32 v[4:5], v[20:21], s[0:1], v[4:5] op_sel_hi:[1,0,1]
	v_pk_fma_f32 v[6:7], v[22:23], s[0:1], v[6:7] op_sel_hi:[1,0,1]
	s_nop 0
	v_cvt_pk_bf16_f32 v24, v0, v1
	v_cvt_pk_bf16_f32 v25, v2, v3
	v_cvt_pk_bf16_f32 v26, v4, v5
	v_cvt_pk_bf16_f32 v27, v6, v7
	global_store_dwordx4 v[204:205], v[24:27], off
	s_nop 1
	ds_read_b128 v[0:3], v14 offset:4352
	ds_read_b128 v[4:7], v14 offset:4368
	s_waitcnt vmcnt(7)
	v_lshlrev_b32_e32 v16, 16, v226
	v_and_b32_e32 v17, 0xffff0000, v226
	v_lshlrev_b32_e32 v18, 16, v227
	v_and_b32_e32 v19, 0xffff0000, v227
	v_lshlrev_b32_e32 v20, 16, v228
	v_and_b32_e32 v21, 0xffff0000, v228
	v_lshlrev_b32_e32 v22, 16, v229
	v_and_b32_e32 v23, 0xffff0000, v229
	s_waitcnt lgkmcnt(0)
	v_pk_mul_f32 v[0:1], v[0:1], v[192:193]
	v_pk_mul_f32 v[2:3], v[2:3], v[194:195]
	v_pk_mul_f32 v[4:5], v[4:5], v[196:197]
	v_pk_mul_f32 v[6:7], v[6:7], v[198:199]
	v_pk_fma_f32 v[0:1], v[16:17], s[0:1], v[0:1] op_sel_hi:[1,0,1]
	v_pk_fma_f32 v[2:3], v[18:19], s[0:1], v[2:3] op_sel_hi:[1,0,1]
	v_pk_fma_f32 v[4:5], v[20:21], s[0:1], v[4:5] op_sel_hi:[1,0,1]
	v_pk_fma_f32 v[6:7], v[22:23], s[0:1], v[6:7] op_sel_hi:[1,0,1]
	s_nop 0
	v_cvt_pk_bf16_f32 v24, v0, v1
	v_cvt_pk_bf16_f32 v25, v2, v3
	v_cvt_pk_bf16_f32 v26, v4, v5
	v_cvt_pk_bf16_f32 v27, v6, v7
	global_store_dwordx4 v[206:207], v[24:27], off
	s_nop 1
	ds_read_b128 v[0:3], v14 offset:6528
	ds_read_b128 v[4:7], v14 offset:6544
	s_waitcnt vmcnt(7)
	v_lshlrev_b32_e32 v16, 16, v230
	v_and_b32_e32 v17, 0xffff0000, v230
	v_lshlrev_b32_e32 v18, 16, v231
	v_and_b32_e32 v19, 0xffff0000, v231
	v_lshlrev_b32_e32 v20, 16, v232
	v_and_b32_e32 v21, 0xffff0000, v232
	v_lshlrev_b32_e32 v22, 16, v233
	v_and_b32_e32 v23, 0xffff0000, v233
	s_waitcnt lgkmcnt(0)
	v_pk_mul_f32 v[0:1], v[0:1], v[192:193]
	v_pk_mul_f32 v[2:3], v[2:3], v[194:195]
	v_pk_mul_f32 v[4:5], v[4:5], v[196:197]
	v_pk_mul_f32 v[6:7], v[6:7], v[198:199]
	v_pk_fma_f32 v[0:1], v[16:17], s[0:1], v[0:1] op_sel_hi:[1,0,1]
	v_pk_fma_f32 v[2:3], v[18:19], s[0:1], v[2:3] op_sel_hi:[1,0,1]
	v_pk_fma_f32 v[4:5], v[20:21], s[0:1], v[4:5] op_sel_hi:[1,0,1]
	v_pk_fma_f32 v[6:7], v[22:23], s[0:1], v[6:7] op_sel_hi:[1,0,1]
	s_nop 0
	v_cvt_pk_bf16_f32 v24, v0, v1
	v_cvt_pk_bf16_f32 v25, v2, v3
	v_cvt_pk_bf16_f32 v26, v4, v5
	v_cvt_pk_bf16_f32 v27, v6, v7
	global_store_dwordx4 v[208:209], v[24:27], off
	s_nop 1
	ds_read_b128 v[0:3], v14 offset:8704
	ds_read_b128 v[4:7], v14 offset:8720
	s_waitcnt vmcnt(7)
	v_lshlrev_b32_e32 v16, 16, v234
	v_and_b32_e32 v17, 0xffff0000, v234
	v_lshlrev_b32_e32 v18, 16, v235
	v_and_b32_e32 v19, 0xffff0000, v235
	v_lshlrev_b32_e32 v20, 16, v236
	v_and_b32_e32 v21, 0xffff0000, v236
	v_lshlrev_b32_e32 v22, 16, v237
	v_and_b32_e32 v23, 0xffff0000, v237
	s_waitcnt lgkmcnt(0)
	v_pk_mul_f32 v[0:1], v[0:1], v[192:193]
	v_pk_mul_f32 v[2:3], v[2:3], v[194:195]
	v_pk_mul_f32 v[4:5], v[4:5], v[196:197]
	v_pk_mul_f32 v[6:7], v[6:7], v[198:199]
	v_pk_fma_f32 v[0:1], v[16:17], s[0:1], v[0:1] op_sel_hi:[1,0,1]
	v_pk_fma_f32 v[2:3], v[18:19], s[0:1], v[2:3] op_sel_hi:[1,0,1]
	v_pk_fma_f32 v[4:5], v[20:21], s[0:1], v[4:5] op_sel_hi:[1,0,1]
	v_pk_fma_f32 v[6:7], v[22:23], s[0:1], v[6:7] op_sel_hi:[1,0,1]
	s_nop 0
	v_cvt_pk_bf16_f32 v24, v0, v1
	v_cvt_pk_bf16_f32 v25, v2, v3
	v_cvt_pk_bf16_f32 v26, v4, v5
	v_cvt_pk_bf16_f32 v27, v6, v7
	global_store_dwordx4 v[210:211], v[24:27], off
	s_nop 1
	ds_read_b128 v[0:3], v14 offset:10880
	ds_read_b128 v[4:7], v14 offset:10896
	s_waitcnt vmcnt(7)
	v_lshlrev_b32_e32 v16, 16, v238
	v_and_b32_e32 v17, 0xffff0000, v238
	v_lshlrev_b32_e32 v18, 16, v239
	v_and_b32_e32 v19, 0xffff0000, v239
	v_lshlrev_b32_e32 v20, 16, v240
	v_and_b32_e32 v21, 0xffff0000, v240
	v_lshlrev_b32_e32 v22, 16, v241
	v_and_b32_e32 v23, 0xffff0000, v241
	s_waitcnt lgkmcnt(0)
	v_pk_mul_f32 v[0:1], v[0:1], v[192:193]
	v_pk_mul_f32 v[2:3], v[2:3], v[194:195]
	v_pk_mul_f32 v[4:5], v[4:5], v[196:197]
	v_pk_mul_f32 v[6:7], v[6:7], v[198:199]
	v_pk_fma_f32 v[0:1], v[16:17], s[0:1], v[0:1] op_sel_hi:[1,0,1]
	v_pk_fma_f32 v[2:3], v[18:19], s[0:1], v[2:3] op_sel_hi:[1,0,1]
	v_pk_fma_f32 v[4:5], v[20:21], s[0:1], v[4:5] op_sel_hi:[1,0,1]
	v_pk_fma_f32 v[6:7], v[22:23], s[0:1], v[6:7] op_sel_hi:[1,0,1]
	s_nop 0
	v_cvt_pk_bf16_f32 v24, v0, v1
	v_cvt_pk_bf16_f32 v25, v2, v3
	v_cvt_pk_bf16_f32 v26, v4, v5
	v_cvt_pk_bf16_f32 v27, v6, v7
	global_store_dwordx4 v[212:213], v[24:27], off
	s_nop 1
	ds_read_b128 v[0:3], v14 offset:13056
	ds_read_b128 v[4:7], v14 offset:13072
	s_waitcnt vmcnt(7)
	v_lshlrev_b32_e32 v16, 16, v242
	v_and_b32_e32 v17, 0xffff0000, v242
	v_lshlrev_b32_e32 v18, 16, v243
	v_and_b32_e32 v19, 0xffff0000, v243
	v_lshlrev_b32_e32 v20, 16, v244
	v_and_b32_e32 v21, 0xffff0000, v244
	v_lshlrev_b32_e32 v22, 16, v245
	v_and_b32_e32 v23, 0xffff0000, v245
	s_waitcnt lgkmcnt(0)
	v_pk_mul_f32 v[0:1], v[0:1], v[192:193]
	v_pk_mul_f32 v[2:3], v[2:3], v[194:195]
	v_pk_mul_f32 v[4:5], v[4:5], v[196:197]
	v_pk_mul_f32 v[6:7], v[6:7], v[198:199]
	v_pk_fma_f32 v[0:1], v[16:17], s[0:1], v[0:1] op_sel_hi:[1,0,1]
	v_pk_fma_f32 v[2:3], v[18:19], s[0:1], v[2:3] op_sel_hi:[1,0,1]
	v_pk_fma_f32 v[4:5], v[20:21], s[0:1], v[4:5] op_sel_hi:[1,0,1]
	v_pk_fma_f32 v[6:7], v[22:23], s[0:1], v[6:7] op_sel_hi:[1,0,1]
	s_nop 0
	v_cvt_pk_bf16_f32 v24, v0, v1
	v_cvt_pk_bf16_f32 v25, v2, v3
	v_cvt_pk_bf16_f32 v26, v4, v5
	v_cvt_pk_bf16_f32 v27, v6, v7
	global_store_dwordx4 v[214:215], v[24:27], off
	s_nop 1
	ds_read_b128 v[0:3], v14 offset:15232
	ds_read_b128 v[4:7], v14 offset:15248
	s_waitcnt vmcnt(7)
	v_lshlrev_b32_e32 v16, 16, v246
	v_and_b32_e32 v17, 0xffff0000, v246
	v_lshlrev_b32_e32 v18, 16, v247
	v_and_b32_e32 v19, 0xffff0000, v247
	v_lshlrev_b32_e32 v20, 16, v248
	v_and_b32_e32 v21, 0xffff0000, v248
	v_lshlrev_b32_e32 v22, 16, v249
	v_and_b32_e32 v23, 0xffff0000, v249
	s_waitcnt lgkmcnt(0)
	v_pk_mul_f32 v[0:1], v[0:1], v[192:193]
	v_pk_mul_f32 v[2:3], v[2:3], v[194:195]
	v_pk_mul_f32 v[4:5], v[4:5], v[196:197]
	v_pk_mul_f32 v[6:7], v[6:7], v[198:199]
	v_pk_fma_f32 v[0:1], v[16:17], s[0:1], v[0:1] op_sel_hi:[1,0,1]
	v_pk_fma_f32 v[2:3], v[18:19], s[0:1], v[2:3] op_sel_hi:[1,0,1]
	v_pk_fma_f32 v[4:5], v[20:21], s[0:1], v[4:5] op_sel_hi:[1,0,1]
	v_pk_fma_f32 v[6:7], v[22:23], s[0:1], v[6:7] op_sel_hi:[1,0,1]
	s_nop 0
	v_cvt_pk_bf16_f32 v24, v0, v1
	v_cvt_pk_bf16_f32 v25, v2, v3
	v_cvt_pk_bf16_f32 v26, v4, v5
	v_cvt_pk_bf16_f32 v27, v6, v7
	global_store_dwordx4 v[216:217], v[24:27], off
	s_nop 1
	s_add_i32 s54, s54, s83
	s_add_i32 s53, s53, s83
	s_cmpk_lt_u32 s54, 0x140
	s_barrier
	s_cbranch_scc1 .LBB0_857

.LBB0_927:
	s_andn2_b64 vcc, exec, s[44:45]
	s_cbranch_vccnz .LBB0_996
	v_readlane_b32 s48, v253, 2
	v_readlane_b32 s49, v253, 3
	v_mov_b32_e32 v6, v133
	v_mov_b32_e32 v0, v133
	v_readlane_b32 s3, v254, 55
	v_ashrrev_i32_e32 v8, 6, v0
	s_nop 0
	v_add_u32_e32 v24, s3, v8
	v_cmp_gt_i32_e32 vcc, s24, v24
	s_and_saveexec_b64 s[46:47], vcc
	s_cbranch_execz .LBB0_933
	s_load_dwordx2 s[44:45], s[48:49], 0xf8
	s_waitcnt lgkmcnt(0)
	s_load_dwordx4 s[52:55], s[48:49], 0x50
	v_ashrrev_i32_e32 v25, 31, v24
	v_lshlrev_b32_e32 v2, 2, v6
	v_lshlrev_b64 v[0:1], 11, v[24:25]
	v_and_b32_e32 v10, 0xfc, v2
	v_lshlrev_b32_e32 v128, 1, v10
	v_lshl_add_u64 v[0:1], s[44:45], 0, v[0:1]
	v_lshl_add_u64 v[2:3], v[0:1], 0, v[128:129]
	s_mov_b64 s[38:39], 0x13600000
	v_lshl_add_u64 v[4:5], v[2:3], 0, s[38:39]
	v_add_co_u32_e32 v2, vcc, s25, v2
	s_mul_i32 s3, s40, 0x36000
	s_nop 0
	v_addc_co_u32_e32 v3, vcc, 0, v3, vcc
	global_load_dwordx2 v[32:33], v[2:3], off
	global_load_dwordx2 v[30:31], v[4:5], off offset:512
	global_load_dwordx2 v[28:29], v[4:5], off offset:1024
	global_load_dwordx2 v[26:27], v[4:5], off offset:1536
	v_and_b32_e32 v2, 64, v188
	v_add_u32_e32 v2, 64, v2
	v_xor_b32_e32 v3, 32, v188
	v_cmp_lt_i32_e32 vcc, v3, v2
	s_add_u32 s3, s44, s3
	s_addc_u32 s30, s45, 0
	v_cndmask_b32_e32 v3, v188, v3, vcc
	v_lshlrev_b32_e32 v34, 2, v3
	v_xor_b32_e32 v3, 16, v188
	v_cmp_lt_i32_e32 vcc, v3, v2
	s_add_u32 s48, s3, 0x13403000
	s_addc_u32 s49, s30, 0
	v_cndmask_b32_e32 v3, v188, v3, vcc
	v_lshlrev_b32_e32 v35, 2, v3
	v_xor_b32_e32 v3, 8, v188
	v_cmp_lt_i32_e32 vcc, v3, v2
	s_lshl_b32 s80, s40, 11
	s_lshl_b64 s[38:39], s[80:81], 2
	v_cndmask_b32_e32 v3, v188, v3, vcc
	v_lshlrev_b32_e32 v36, 2, v3
	v_xor_b32_e32 v3, 4, v188
	v_cmp_lt_i32_e32 vcc, v3, v2
	s_waitcnt lgkmcnt(0)
	s_add_u32 s50, s54, s38
	v_readlane_b32 s3, v254, 56
	v_cndmask_b32_e32 v3, v188, v3, vcc
	v_lshlrev_b32_e32 v37, 2, v3
	v_xor_b32_e32 v3, 2, v188
	v_cmp_lt_i32_e32 vcc, v3, v2
	s_addc_u32 s51, s55, s39
	v_add_u32_e32 v8, s3, v8
	v_cndmask_b32_e32 v3, v188, v3, vcc
	v_lshlrev_b32_e32 v38, 2, v3
	v_xor_b32_e32 v3, 1, v188
	s_add_u32 s38, s52, s38
	v_cmp_lt_i32_e32 vcc, v3, v2
	v_ashrrev_i32_e32 v9, 31, v8
	s_addc_u32 s39, s53, s39
	v_cndmask_b32_e32 v2, v188, v3, vcc
	v_lshlrev_b32_e32 v128, 2, v10
	v_or_b32_e32 v12, 0x100, v10
	v_or_b32_e32 v14, 0x200, v10
	v_or_b32_e32 v16, 0x300, v10
	v_and_b32_e32 v6, 63, v6
	v_lshlrev_b64 v[8:9], 11, v[8:9]
	v_lshlrev_b32_e32 v39, 2, v2
	v_lshl_add_u64 v[2:3], s[38:39], 0, v[128:129]
	v_lshl_add_u64 v[4:5], s[50:51], 0, v[128:129]
	v_lshlrev_b32_e32 v6, 3, v6
	v_mov_b32_e32 v7, v129
	v_lshl_add_u64 v[8:9], s[44:45], 0, v[8:9]
	s_mov_b64 s[50:51], 0
	v_lshlrev_b32_e32 v128, 2, v10
	v_lshlrev_b32_e32 v10, 2, v12
	v_lshlrev_b32_e32 v12, 2, v14
	v_lshlrev_b32_e32 v14, 2, v16
	v_cmp_lt_i32_e32 vcc, s22, v24
	v_add_u32_e32 v216, 0xffffe000, v24
	v_lshrrev_b32_e32 v216, 12, v216
	v_add_u32_e32 v216, 1, v216
	s_nop 0
	v_cndmask_b32_e32 v216, 0, v216, vcc
	v_mov_b64_e32 v[212:213], s[48:49]
	v_mad_u64_u32 v[212:213], s[38:39], v216, s23, v[212:213]
	s_mov_b64 s[38:39], 0x1000
	v_lshl_add_u64 v[212:213], v[212:213], 0, v[128:129]
	v_lshl_add_u64 v[214:215], v[212:213], 0, s[38:39]
	global_load_dwordx4 v[96:99], v[2:3], off
	global_load_dwordx4 v[112:115], v[4:5], off
	global_load_dwordx4 v[136:139], v[212:213], off
	global_load_dwordx4 v[152:155], v[214:215], off
	global_load_dwordx4 v[100:103], v[2:3], off offset:1024
	global_load_dwordx4 v[116:119], v[4:5], off offset:1024
	global_load_dwordx4 v[140:143], v[212:213], off offset:1024
	global_load_dwordx4 v[156:159], v[214:215], off offset:1024
	global_load_dwordx4 v[104:107], v[2:3], off offset:2048
	global_load_dwordx4 v[120:123], v[4:5], off offset:2048
	global_load_dwordx4 v[144:147], v[212:213], off offset:2048
	global_load_dwordx4 v[160:163], v[214:215], off offset:2048
	global_load_dwordx4 v[108:111], v[2:3], off offset:3072
	global_load_dwordx4 v[124:127], v[4:5], off offset:3072
	global_load_dwordx4 v[148:151], v[212:213], off offset:3072
	global_load_dwordx4 v[164:167], v[214:215], off offset:3072
	s_waitcnt vmcnt(16)
	s_branch .LBB0_931
.LBB0_930:
	s_or_b64 exec, exec, s[52:53]
	v_lshlrev_b32_e32 v54, 16, v32
	v_and_b32_e32 v55, 0xffff0000, v32
	v_add_f32_e32 v11, 0, v54
	v_lshlrev_b32_e32 v32, 16, v33
	v_add_f32_e32 v11, v11, v55
	v_and_b32_e32 v33, 0xffff0000, v33
	v_add_f32_e32 v11, v11, v32
	v_lshlrev_b32_e32 v56, 16, v30
	v_add_f32_e32 v11, v11, v33
	v_and_b32_e32 v57, 0xffff0000, v30
	v_add_f32_e32 v11, v11, v56
	v_lshlrev_b32_e32 v30, 16, v31
	v_add_f32_e32 v11, v11, v57
	v_and_b32_e32 v31, 0xffff0000, v31
	v_add_f32_e32 v11, v11, v30
	v_lshlrev_b32_e32 v58, 16, v28
	v_add_f32_e32 v11, v11, v31
	v_and_b32_e32 v59, 0xffff0000, v28
	v_add_f32_e32 v11, v11, v58
	v_lshlrev_b32_e32 v60, 16, v29
	v_add_f32_e32 v11, v11, v59
	v_and_b32_e32 v61, 0xffff0000, v29
	v_add_f32_e32 v11, v11, v60
	v_lshlrev_b32_e32 v62, 16, v26
	v_add_f32_e32 v11, v11, v61
	v_and_b32_e32 v63, 0xffff0000, v26
	v_add_f32_e32 v11, v11, v62
	v_lshlrev_b32_e32 v64, 16, v27
	v_add_f32_e32 v11, v11, v63
	v_and_b32_e32 v65, 0xffff0000, v27
	v_add_f32_e32 v11, v11, v64
	v_add_f32_e32 v11, v11, v65
	ds_bpermute_b32 v13, v34, v11
	v_cmp_lt_i32_e32 vcc, s22, v24
	s_and_b64 s[38:39], exec, s[44:45]
	s_or_b64 s[50:51], s[38:39], s[50:51]
	s_waitcnt lgkmcnt(0)
	v_add_f32_e32 v11, v11, v13
	ds_bpermute_b32 v13, v35, v11
	v_lshl_add_u64 v[78:79], v[0:1], 0, v[6:7]
	s_mov_b32 s3, 0x1d600000
	v_mov_b32_e32 v15, v129
	v_lshl_add_u64 v[8:9], v[8:9], 0, s[4:5]
	s_waitcnt lgkmcnt(0)
	v_add_f32_e32 v11, v11, v13
	ds_bpermute_b32 v13, v36, v11
	v_lshl_add_u64 v[0:1], v[0:1], 0, s[4:5]
	s_waitcnt lgkmcnt(0)
	v_add_f32_e32 v11, v11, v13
	ds_bpermute_b32 v13, v37, v11
	s_waitcnt lgkmcnt(0)
	v_add_f32_e32 v11, v11, v13
	ds_bpermute_b32 v13, v38, v11
	s_waitcnt lgkmcnt(0)
	v_add_f32_e32 v11, v11, v13
	ds_bpermute_b32 v13, v39, v11
	s_waitcnt lgkmcnt(0)
	v_add_f32_e32 v11, v11, v13
	v_mul_f32_e32 v66, 0x3a800000, v11
	v_add_u32_e32 v11, 0xffffe000, v24
	v_lshrrev_b32_e32 v11, 12, v11
	v_add_u32_e32 v11, 1, v11
	v_cndmask_b32_e32 v11, 0, v11, vcc
	v_mov_b64_e32 v[24:25], s[48:49]
	v_mad_u64_u32 v[24:25], s[38:39], v11, s23, v[24:25]
	s_mov_b64 s[38:39], 0x1000
	s_nop 0
	v_lshl_add_u64 v[68:69], v[24:25], 0, s[38:39]
	v_lshl_add_u64 v[24:25], v[24:25], 0, v[128:129]
	v_lshl_add_u64 v[26:27], v[68:69], 0, v[128:129]
	v_pk_add_f32 v[54:55], v[54:55], v[66:67] op_sel_hi:[1,0] neg_lo:[0,1] neg_hi:[0,1]
	v_pk_add_f32 v[32:33], v[32:33], v[66:67] op_sel_hi:[1,0] neg_lo:[0,1] neg_hi:[0,1]
	v_pk_mul_f32 v[72:73], v[54:55], v[54:55]
	v_mov_b32_e32 v11, v129
	v_pk_mul_f32 v[70:71], v[32:33], v[32:33]
	v_lshl_add_u64 v[80:81], v[68:69], 0, v[10:11]
	v_add_f32_e32 v11, v72, v73
	v_pk_add_f32 v[56:57], v[56:57], v[66:67] op_sel_hi:[1,0] neg_lo:[0,1] neg_hi:[0,1]
	v_add_f32_e32 v11, v70, v11
	v_pk_mul_f32 v[86:87], v[56:57], v[56:57]
	v_add_f32_e32 v11, v71, v11
	v_pk_add_f32 v[82:83], v[30:31], v[66:67] op_sel_hi:[1,0] neg_lo:[0,1] neg_hi:[0,1]
	v_add_f32_e32 v11, v86, v11
	v_pk_mul_f32 v[84:85], v[82:83], v[82:83]
	v_add_f32_e32 v11, v87, v11
	v_pk_add_f32 v[58:59], v[58:59], v[66:67] op_sel_hi:[1,0] neg_lo:[0,1] neg_hi:[0,1]
	v_add_f32_e32 v11, v84, v11
	v_pk_mul_f32 v[92:93], v[58:59], v[58:59]
	v_add_f32_e32 v11, v85, v11
	v_pk_add_f32 v[60:61], v[60:61], v[66:67] op_sel_hi:[1,0] neg_lo:[0,1] neg_hi:[0,1]
	v_add_f32_e32 v11, v92, v11
	v_pk_mul_f32 v[90:91], v[60:61], v[60:61]
	v_add_f32_e32 v11, v93, v11
	v_pk_add_f32 v[30:31], v[62:63], v[66:67] op_sel_hi:[1,0] neg_lo:[0,1] neg_hi:[0,1]
	v_add_f32_e32 v11, v90, v11
	v_pk_mul_f32 v[62:63], v[30:31], v[30:31]
	v_add_f32_e32 v11, v91, v11
	v_add_f32_e32 v11, v62, v11
	v_add_f32_e32 v11, v63, v11
	v_mov_b32_e32 v13, v129
	v_lshl_add_u64 v[88:89], v[68:69], 0, v[12:13]
	v_pk_add_f32 v[28:29], v[64:65], v[66:67] op_sel_hi:[1,0] neg_lo:[0,1] neg_hi:[0,1]
	v_pk_mul_f32 v[64:65], v[28:29], v[28:29]
	v_lshl_add_u64 v[26:27], v[68:69], 0, v[14:15]
	v_add_f32_e32 v11, v64, v11
	v_add_f32_e32 v11, v65, v11
	ds_bpermute_b32 v13, v34, v11
	s_waitcnt lgkmcnt(0)
	v_add_f32_e32 v11, v11, v13
	ds_bpermute_b32 v13, v35, v11
	s_waitcnt lgkmcnt(0)
	v_add_f32_e32 v11, v11, v13
	ds_bpermute_b32 v13, v36, v11
	s_waitcnt lgkmcnt(0)
	v_add_f32_e32 v11, v11, v13
	ds_bpermute_b32 v13, v37, v11
	s_waitcnt lgkmcnt(0)
	v_add_f32_e32 v11, v11, v13
	ds_bpermute_b32 v13, v38, v11
	s_waitcnt lgkmcnt(0)
	v_add_f32_e32 v11, v11, v13
	ds_bpermute_b32 v13, v39, v11
	s_waitcnt lgkmcnt(0)
	v_add_f32_e32 v11, v11, v13
	v_fmamk_f32 v11, v11, 0x3a800000, v182
	v_cmp_gt_f32_e32 vcc, s13, v11
	v_mul_f32_e32 v13, 0x4b800000, v11
	s_nop 0
	v_cndmask_b32_e32 v11, v11, v13, vcc
	v_rsq_f32_e32 v11, v11
	s_nop 0
	v_mul_f32_e32 v13, 0x45800000, v11
	v_cndmask_b32_e32 v62, v11, v13, vcc
	s_waitcnt vmcnt(4)
	v_pk_mul_f32 v[168:169], v[54:55], v[62:63] op_sel_hi:[1,0]
	v_pk_mul_f32 v[170:171], v[32:33], v[62:63] op_sel_hi:[1,0]
	v_add_co_u32_e32 v32, vcc, s25, v78
	s_nop 1
	v_addc_co_u32_e32 v33, vcc, 0, v79, vcc
	v_add_co_u32_e32 v50, vcc, s3, v78
	s_nop 1
	v_addc_co_u32_e32 v51, vcc, 0, v79, vcc
	v_pk_add_f32 v[172:173], v[152:153], 1.0 op_sel_hi:[1,0]
	v_pk_add_f32 v[174:175], v[154:155], 1.0 op_sel_hi:[1,0]
	v_pk_fma_f32 v[168:169], v[96:97], v[168:169], v[112:113]
	v_pk_fma_f32 v[170:171], v[98:99], v[170:171], v[114:115]
	s_nop 0
	v_pk_fma_f32 v[192:193], v[172:173], v[168:169], v[136:137]
	v_pk_fma_f32 v[194:195], v[174:175], v[170:171], v[138:139]
	v_cvt_pk_bf16_f32 v196, v168, v169
	v_cvt_pk_bf16_f32 v197, v170, v171
	v_cvt_pk_bf16_f32 v198, v192, v193
	v_cvt_pk_bf16_f32 v199, v194, v195
	global_store_dwordx2 v[32:33], v[196:197], off
	global_store_dwordx2 v[50:51], v[198:199], off
	v_pk_mul_f32 v[168:169], v[56:57], v[62:63] op_sel_hi:[1,0]
	v_pk_mul_f32 v[170:171], v[82:83], v[62:63] op_sel_hi:[1,0]
	v_pk_add_f32 v[172:173], v[156:157], 1.0 op_sel_hi:[1,0]
	v_pk_add_f32 v[174:175], v[158:159], 1.0 op_sel_hi:[1,0]
	v_pk_fma_f32 v[168:169], v[100:101], v[168:169], v[116:117]
	v_pk_fma_f32 v[170:171], v[102:103], v[170:171], v[118:119]
	s_nop 0
	v_pk_fma_f32 v[192:193], v[172:173], v[168:169], v[140:141]
	v_pk_fma_f32 v[194:195], v[174:175], v[170:171], v[142:143]
	v_cvt_pk_bf16_f32 v200, v168, v169
	v_cvt_pk_bf16_f32 v201, v170, v171
	v_cvt_pk_bf16_f32 v202, v192, v193
	v_cvt_pk_bf16_f32 v203, v194, v195
	global_store_dwordx2 v[32:33], v[200:201], off offset:512
	global_store_dwordx2 v[50:51], v[202:203], off offset:512
	v_pk_mul_f32 v[168:169], v[58:59], v[62:63] op_sel_hi:[1,0]
	v_pk_mul_f32 v[170:171], v[60:61], v[62:63] op_sel_hi:[1,0]
	v_pk_add_f32 v[172:173], v[160:161], 1.0 op_sel_hi:[1,0]
	v_pk_add_f32 v[174:175], v[162:163], 1.0 op_sel_hi:[1,0]
	v_pk_fma_f32 v[168:169], v[104:105], v[168:169], v[120:121]
	v_pk_fma_f32 v[170:171], v[106:107], v[170:171], v[122:123]
	s_nop 0
	v_pk_fma_f32 v[192:193], v[172:173], v[168:169], v[144:145]
	v_pk_fma_f32 v[194:195], v[174:175], v[170:171], v[146:147]
	v_cvt_pk_bf16_f32 v204, v168, v169
	v_cvt_pk_bf16_f32 v205, v170, v171
	v_cvt_pk_bf16_f32 v206, v192, v193
	v_cvt_pk_bf16_f32 v207, v194, v195
	global_store_dwordx2 v[32:33], v[204:205], off offset:1024
	global_store_dwordx2 v[50:51], v[206:207], off offset:1024
	v_pk_mul_f32 v[168:169], v[30:31], v[62:63] op_sel_hi:[1,0]
	v_pk_mul_f32 v[170:171], v[28:29], v[62:63] op_sel_hi:[1,0]
	v_pk_add_f32 v[172:173], v[164:165], 1.0 op_sel_hi:[1,0]
	v_pk_add_f32 v[174:175], v[166:167], 1.0 op_sel_hi:[1,0]
	v_pk_fma_f32 v[168:169], v[108:109], v[168:169], v[124:125]
	v_pk_fma_f32 v[170:171], v[110:111], v[170:171], v[126:127]
	s_nop 0
	v_pk_fma_f32 v[192:193], v[172:173], v[168:169], v[148:149]
	v_pk_fma_f32 v[194:195], v[174:175], v[170:171], v[150:151]
	v_cvt_pk_bf16_f32 v208, v168, v169
	v_cvt_pk_bf16_f32 v209, v170, v171
	v_cvt_pk_bf16_f32 v210, v192, v193
	v_cvt_pk_bf16_f32 v211, v194, v195
	global_store_dwordx2 v[32:33], v[208:209], off offset:1536
	global_store_dwordx2 v[50:51], v[210:211], off offset:1536
	v_cmp_lt_i32_e32 vcc, s22, v40
	v_add_u32_e32 v216, 0xffffe000, v40
	v_lshrrev_b32_e32 v216, 12, v216
	v_add_u32_e32 v216, 1, v216
	s_nop 0
	v_cndmask_b32_e32 v216, 0, v216, vcc
	v_mov_b64_e32 v[212:213], s[48:49]
	v_mad_u64_u32 v[212:213], s[38:39], v216, s23, v[212:213]
	s_mov_b64 s[38:39], 0x1000
	v_lshl_add_u64 v[212:213], v[212:213], 0, v[128:129]
	v_lshl_add_u64 v[214:215], v[212:213], 0, s[38:39]
	global_load_dwordx4 v[96:99], v[2:3], off
	global_load_dwordx4 v[112:115], v[4:5], off
	global_load_dwordx4 v[136:139], v[212:213], off
	global_load_dwordx4 v[152:155], v[214:215], off
	global_load_dwordx4 v[100:103], v[2:3], off offset:1024
	global_load_dwordx4 v[116:119], v[4:5], off offset:1024
	global_load_dwordx4 v[140:143], v[212:213], off offset:1024
	global_load_dwordx4 v[156:159], v[214:215], off offset:1024
	global_load_dwordx4 v[104:107], v[2:3], off offset:2048
	global_load_dwordx4 v[120:123], v[4:5], off offset:2048
	global_load_dwordx4 v[144:147], v[212:213], off offset:2048
	global_load_dwordx4 v[160:163], v[214:215], off offset:2048
	global_load_dwordx4 v[108:111], v[2:3], off offset:3072
	global_load_dwordx4 v[124:127], v[4:5], off offset:3072
	global_load_dwordx4 v[148:151], v[212:213], off offset:3072
	global_load_dwordx4 v[164:167], v[214:215], off offset:3072
	s_waitcnt vmcnt(24)
	v_mov_b32_e32 v24, v40
	v_mov_b32_e32 v32, v18
	v_mov_b32_e32 v33, v19
	v_mov_b32_e32 v30, v20
	v_mov_b32_e32 v31, v21
	v_mov_b32_e32 v28, v22
	v_mov_b32_e32 v29, v23
	v_mov_b32_e32 v26, v16
	v_mov_b32_e32 v27, v17
	s_andn2_b64 exec, exec, s[50:51]
	s_cbranch_execz .LBB0_933
.LBB0_931:
	v_add_u32_e32 v40, s84, v24
	v_cmp_gt_i32_e32 vcc, s24, v40
	v_cmp_lt_i32_e64 s[44:45], s26, v40
	v_mov_b32_e32 v18, v32
	v_mov_b32_e32 v19, v33
	v_mov_b32_e32 v20, v30
	v_mov_b32_e32 v21, v31
	v_mov_b32_e32 v22, v28
	v_mov_b32_e32 v23, v29
	v_mov_b32_e32 v16, v26
	v_mov_b32_e32 v17, v27
	s_mov_b64 s[52:53], exec
	v_lshl_add_u64 v[16:17], v[8:9], 0, v[6:7]
	v_add_co_u32_e32 v16, vcc, 0x13600000, v16
	s_nop 1
	v_addc_co_u32_e32 v17, vcc, 0, v17, vcc
	global_load_dwordx2 v[18:19], v[16:17], off
	global_load_dwordx2 v[20:21], v[16:17], off offset:512
	global_load_dwordx2 v[22:23], v[16:17], off offset:1024
	s_nop 0
	global_load_dwordx2 v[16:17], v[16:17], off offset:1536
	s_branch .LBB0_930

.LBB0_1113:
	s_and_saveexec_b64 s[64:65], vcc
	s_cbranch_execz .LBB0_1112
	global_load_dword v130, v[92:93], off
	global_load_dword v131, v[92:93], off offset:256
	global_load_dword v89, v[94:95], off sc1
	global_load_dword v108, v[94:95], off offset:256 sc1
	s_and_b64 exec, exec, s[42:43]
	s_cbranch_execz .LBB0_1112
	s_lshl_b32 s80, s2, 8
	s_lshl_b32 s38, s2, 9
	s_mov_b32 s39, s81
	s_lshl_b64 s[52:53], s[80:81], 2
	v_lshl_add_u64 v[0:1], v[98:99], 0, s[52:53]
	v_lshl_add_u64 v[4:5], v[96:97], 0, s[38:39]
	global_load_dwordx4 v[0:3], v[0:1], off
	s_lshl_b32 s80, s2, 21
	global_load_dwordx2 v[4:5], v[4:5], off
	v_lshl_add_u64 v[110:111], v[100:101], 0, s[38:39]
	v_lshl_add_u64 v[112:113], v[102:103], 0, s[52:53]
	v_lshl_add_u64 v[114:115], v[90:91], 0, s[80:81]
	s_mov_b32 s3, 0
	s_mov_b64 s[66:67], 0
	v_mov_b32_e32 v120, v88
	s_waitcnt vmcnt(0)
	v_mov_b32_e32 v142, v4
	v_mov_b32_e32 v143, v5
	v_lshlrev_b32_e32 v116, 16, v4
	v_and_b32_e32 v117, 0xffff0000, v4
	v_lshlrev_b32_e32 v118, 16, v5
	v_and_b32_e32 v119, 0xffff0000, v5
	v_mov_b64_e32 v[6:7], v[2:3]
	v_mov_b64_e32 v[4:5], v[0:1]
	ds_write2st64_b32 v122, v130, v131 offset0:68 offset1:69
	v_add_u32_e32 v62, 0x4400, v123
	ds_read2_b32 v[8:9], v62 offset0:0 offset1:8
	ds_read2_b32 v[10:11], v62 offset0:16 offset1:24
	ds_read2_b32 v[12:13], v62 offset0:32 offset1:40
	ds_read2_b32 v[14:15], v62 offset0:48 offset1:56
	ds_read2_b32 v[16:17], v62 offset0:64 offset1:72
	ds_read2_b32 v[18:19], v62 offset0:80 offset1:88
	ds_read2_b32 v[20:21], v62 offset0:96 offset1:104
	ds_read2_b32 v[22:23], v62 offset0:112 offset1:120
	s_waitcnt lgkmcnt(7)
	v_ashrrev_i32_e32 v57, 31, v8
	v_mov_b32_e32 v56, v8
	v_lshlrev_b64 v[56:57], 7, v[56:57]
	v_lshl_add_u64 v[24:25], v[114:115], 0, v[56:57]
	global_load_dwordx4 v[144:147], v[24:25], off
	v_ashrrev_i32_e32 v57, 31, v9
	v_mov_b32_e32 v56, v9
	v_lshlrev_b64 v[56:57], 7, v[56:57]
	v_lshl_add_u64 v[26:27], v[114:115], 0, v[56:57]
	global_load_dwordx4 v[148:151], v[26:27], off
	s_waitcnt lgkmcnt(6)
	v_ashrrev_i32_e32 v57, 31, v10
	v_mov_b32_e32 v56, v10
	v_lshlrev_b64 v[56:57], 7, v[56:57]
	v_lshl_add_u64 v[28:29], v[114:115], 0, v[56:57]
	global_load_dwordx4 v[152:155], v[28:29], off
	v_ashrrev_i32_e32 v57, 31, v11
	v_mov_b32_e32 v56, v11
	v_lshlrev_b64 v[56:57], 7, v[56:57]
	v_lshl_add_u64 v[30:31], v[114:115], 0, v[56:57]
	global_load_dwordx4 v[156:159], v[30:31], off
	s_waitcnt lgkmcnt(5)
	v_ashrrev_i32_e32 v57, 31, v12
	v_mov_b32_e32 v56, v12
	v_lshlrev_b64 v[56:57], 7, v[56:57]
	v_lshl_add_u64 v[32:33], v[114:115], 0, v[56:57]
	global_load_dwordx4 v[160:163], v[32:33], off
	v_ashrrev_i32_e32 v57, 31, v13
	v_mov_b32_e32 v56, v13
	v_lshlrev_b64 v[56:57], 7, v[56:57]
	v_lshl_add_u64 v[34:35], v[114:115], 0, v[56:57]
	global_load_dwordx4 v[164:167], v[34:35], off
	s_waitcnt lgkmcnt(4)
	v_ashrrev_i32_e32 v57, 31, v14
	v_mov_b32_e32 v56, v14
	v_lshlrev_b64 v[56:57], 7, v[56:57]
	v_lshl_add_u64 v[36:37], v[114:115], 0, v[56:57]
	global_load_dwordx4 v[168:171], v[36:37], off
	v_ashrrev_i32_e32 v57, 31, v15
	v_mov_b32_e32 v56, v15
	v_lshlrev_b64 v[56:57], 7, v[56:57]
	v_lshl_add_u64 v[38:39], v[114:115], 0, v[56:57]
	global_load_dwordx4 v[172:175], v[38:39], off
	s_waitcnt lgkmcnt(3)
	v_ashrrev_i32_e32 v57, 31, v16
	v_mov_b32_e32 v56, v16
	v_lshlrev_b64 v[56:57], 7, v[56:57]
	v_lshl_add_u64 v[40:41], v[114:115], 0, v[56:57]
	global_load_dwordx4 v[192:195], v[40:41], off
	v_ashrrev_i32_e32 v57, 31, v17
	v_mov_b32_e32 v56, v17
	v_lshlrev_b64 v[56:57], 7, v[56:57]
	v_lshl_add_u64 v[42:43], v[114:115], 0, v[56:57]
	global_load_dwordx4 v[196:199], v[42:43], off
	s_waitcnt lgkmcnt(2)
	v_ashrrev_i32_e32 v57, 31, v18
	v_mov_b32_e32 v56, v18
	v_lshlrev_b64 v[56:57], 7, v[56:57]
	v_lshl_add_u64 v[44:45], v[114:115], 0, v[56:57]
	global_load_dwordx4 v[200:203], v[44:45], off
	v_ashrrev_i32_e32 v57, 31, v19
	v_mov_b32_e32 v56, v19
	v_lshlrev_b64 v[56:57], 7, v[56:57]
	v_lshl_add_u64 v[46:47], v[114:115], 0, v[56:57]
	global_load_dwordx4 v[204:207], v[46:47], off
	s_waitcnt lgkmcnt(1)
	v_ashrrev_i32_e32 v57, 31, v20
	v_mov_b32_e32 v56, v20
	v_lshlrev_b64 v[56:57], 7, v[56:57]
	v_lshl_add_u64 v[48:49], v[114:115], 0, v[56:57]
	global_load_dwordx4 v[208:211], v[48:49], off
	v_ashrrev_i32_e32 v57, 31, v21
	v_mov_b32_e32 v56, v21
	v_lshlrev_b64 v[56:57], 7, v[56:57]
	v_lshl_add_u64 v[50:51], v[114:115], 0, v[56:57]
	global_load_dwordx4 v[212:215], v[50:51], off
	s_waitcnt lgkmcnt(0)
	v_ashrrev_i32_e32 v57, 31, v22
	v_mov_b32_e32 v56, v22
	v_lshlrev_b64 v[56:57], 7, v[56:57]
	v_lshl_add_u64 v[52:53], v[114:115], 0, v[56:57]
	global_load_dwordx4 v[216:219], v[52:53], off
	v_ashrrev_i32_e32 v57, 31, v23
	v_mov_b32_e32 v56, v23
	v_lshlrev_b64 v[56:57], 7, v[56:57]
	v_lshl_add_u64 v[54:55], v[114:115], 0, v[56:57]
	global_load_dwordx4 v[220:223], v[54:55], off
	v_cmp_lt_i32_e64 s[74:75], 1, v109
	s_and_saveexec_b64 s[72:73], s[74:75]
	s_cbranch_execz .Lgv_pro_noidx
	v_add_u32_e32 v58, s84, v120
	v_ashrrev_i32_e32 v59, 31, v58
	v_lshlrev_b64 v[58:59], 9, v[58:59]
	v_lshl_add_u64 v[58:59], v[104:105], 0, v[58:59]
	global_load_dword v130, v[58:59], off
	global_load_dword v131, v[58:59], off offset:256
.Lgv_pro_noidx:
	s_or_b64 exec, exec, s[72:73]
	global_load_dword v141, v[92:93], off
	s_branch .LBB0_1117
.LBB0_1116:
	s_or_b64 exec, exec, s[52:53]
	s_waitcnt lgkmcnt(0)
	s_nop 3
	ds_read_b128 v[8:11], v128
	v_pk_add_f32 v[0:1], v[0:1], 1.0 op_sel_hi:[1,0]
	v_pk_add_f32 v[2:3], v[2:3], 1.0 op_sel_hi:[1,0]
	v_ashrrev_i32_e32 v121, 31, v120
	v_cmp_eq_u32_e64 s[52:53], s3, v109
	s_waitcnt lgkmcnt(0)
	v_pk_mul_f32 v[0:1], v[0:1], v[8:9]
	v_pk_mul_f32 v[2:3], v[2:3], v[10:11]
	v_pk_mul_f32 v[0:1], v[0:1], s[90:91] op_sel_hi:[1,0]
	v_pk_mul_f32 v[2:3], v[2:3], s[90:91] op_sel_hi:[1,0]
	v_pk_fma_f32 v[0:1], v[116:117], s[0:1], v[0:1] op_sel_hi:[1,0,1]
	v_pk_fma_f32 v[2:3], v[118:119], s[0:1], v[2:3] op_sel_hi:[1,0,1]
	v_cvt_pk_bf16_f32 v0, v0, v1
	v_cvt_pk_bf16_f32 v1, v2, v3
	v_lshlrev_b64 v[2:3], 11, v[120:121]
	v_lshl_add_u64 v[2:3], v[110:111], 0, v[2:3]
	global_store_dwordx2 v[2:3], v[0:1], off
	v_add_u32_e32 v120, s84, v120
	s_or_b64 s[66:67], s[52:53], s[66:67]
	s_andn2_b64 exec, exec, s[66:67]
	s_cbranch_execz .LBB0_1112
.LBB0_1117:
	s_waitcnt vmcnt(17)
	v_mov_b64_e32 v[0:1], v[4:5]
	v_mov_b64_e32 v[2:3], v[6:7]
	v_lshlrev_b32_e32 v116, 16, v142
	v_and_b32_e32 v117, 0xffff0000, v142
	v_lshlrev_b32_e32 v118, 16, v143
	v_and_b32_e32 v119, 0xffff0000, v143
	ds_write2st64_b32 v122, v89, v108 offset0:70 offset1:71
	s_add_i32 s3, s3, 1
.LBB0_1119:
	ds_read_b128 v[72:75], v124 offset:17920
	ds_read_b128 v[80:83], v124 offset:17936
	s_waitcnt lgkmcnt(1)
	v_pk_mul_f32 v[78:79], v[72:73], s[82:83] op_sel_hi:[1,0]
	s_waitcnt lgkmcnt(0)
	v_pk_mul_f32 v[72:73], v[80:81], s[82:83] op_sel_hi:[1,0]
	v_mov_b32_e32 v80, 0
	v_pk_mul_f32 v[76:77], v[74:75], s[82:83] op_sel_hi:[1,0]
	v_cvt_scalef32_pk_fp4_f32 v80, v78, v79, 1.0
	v_cvt_scalef32_pk_fp4_f32 v80, v76, v77, 1.0 op_sel:[0,0,1,0]
	v_pk_mul_f32 v[74:75], v[82:83], s[82:83] op_sel_hi:[1,0]
	v_cvt_scalef32_pk_fp4_f32 v80, v72, v73, 1.0 op_sel:[0,0,0,1]
	s_nop 0
	v_cvt_scalef32_pk_fp4_f32 v80, v74, v75, 1.0 op_sel:[0,0,1,1]
	s_and_saveexec_b64 s[52:53], s[44:45]
	s_cbranch_execz .LBB0_1125
	v_cvt_scalef32_pk_f32_fp4 v[82:83], v80, 1.0
	v_pk_add_f32 v[78:79], v[78:79], v[82:83] neg_lo:[0,1] neg_hi:[0,1]
	v_cvt_scalef32_pk_f32_fp4 v[82:83], v80, 1.0 op_sel:[1,0,0]
	v_pk_add_f32 v[76:77], v[76:77], v[82:83] neg_lo:[0,1] neg_hi:[0,1]
	v_cvt_scalef32_pk_f32_fp4 v[82:83], v80, 1.0 op_sel:[0,1,0]
	v_cvt_scalef32_pk_f32_fp4 v[80:81], v80, 1.0 op_sel:[1,1,0]
	v_pk_mul_f32 v[78:79], v[78:79], 4.0 op_sel_hi:[1,0]
	v_pk_add_f32 v[74:75], v[74:75], v[80:81] neg_lo:[0,1] neg_hi:[0,1]
	v_mov_b32_e32 v80, v129
	v_pk_mul_f32 v[76:77], v[76:77], 4.0 op_sel_hi:[1,0]
	v_pk_add_f32 v[72:73], v[72:73], v[82:83] neg_lo:[0,1] neg_hi:[0,1]
	v_cvt_scalef32_pk_fp4_f32 v80, v78, v79, 1.0
	v_pk_mul_f32 v[72:73], v[72:73], 4.0 op_sel_hi:[1,0]
	v_cvt_scalef32_pk_fp4_f32 v80, v76, v77, 1.0 op_sel:[0,0,1,0]
	v_pk_mul_f32 v[74:75], v[74:75], 4.0 op_sel_hi:[1,0]
	v_cvt_scalef32_pk_fp4_f32 v80, v72, v73, 1.0 op_sel:[0,0,0,1]
	s_nop 0
	v_cvt_scalef32_pk_fp4_f32 v80, v74, v75, 1.0 op_sel:[0,0,1,1]
	s_or_b64 exec, exec, s[52:53]
	s_and_saveexec_b64 s[52:53], s[46:47]
	s_cbranch_execnz .LBB0_1126

.LBB0_1123:
	s_or_b64 exec, exec, s[52:53]
	ds_write_b32 v122, v80 offset:17408
	ds_read_b128 v[84:87], v125 offset:17408
	ds_read_b128 v[80:83], v125 offset:17424
	ds_read_b128 v[76:79], v125 offset:17440
	ds_read_b128 v[72:75], v125 offset:17456
	s_waitcnt vmcnt(16)
	ds_write2_b64 v126, v[144:145], v[146:147] offset1:1
	s_waitcnt vmcnt(15)
	ds_write2_b64 v126, v[148:149], v[150:151] offset0:136 offset1:137
	s_waitcnt vmcnt(14)
	v_add_u32_e32 v8, 0x880, v126
	ds_write2_b64 v8, v[152:153], v[154:155] offset1:1
	s_waitcnt vmcnt(13)
	v_add_u32_e32 v8, 0xcc0, v126
	ds_write2_b64 v8, v[156:157], v[158:159] offset1:1
	s_waitcnt vmcnt(12)
	v_add_u32_e32 v8, 0x1100, v126
	ds_write2_b64 v8, v[160:161], v[162:163] offset1:1
	s_waitcnt vmcnt(11)
	v_add_u32_e32 v8, 0x1540, v126
	ds_write2_b64 v8, v[164:165], v[166:167] offset1:1
	s_waitcnt vmcnt(10)
	v_add_u32_e32 v8, 0x1980, v126
	ds_write2_b64 v8, v[168:169], v[170:171] offset1:1
	s_waitcnt vmcnt(9)
	v_add_u32_e32 v8, 0x1dc0, v126
	ds_write2_b64 v8, v[172:173], v[174:175] offset1:1
	s_waitcnt vmcnt(8)
	v_add_u32_e32 v8, 0x2200, v126
	ds_write2_b64 v8, v[192:193], v[194:195] offset1:1
	s_waitcnt vmcnt(7)
	v_add_u32_e32 v8, 0x2640, v126
	ds_write2_b64 v8, v[196:197], v[198:199] offset1:1
	s_waitcnt vmcnt(6)
	v_add_u32_e32 v8, 0x2a80, v126
	ds_write2_b64 v8, v[200:201], v[202:203] offset1:1
	s_waitcnt vmcnt(5)
	v_add_u32_e32 v8, 0x2ec0, v126
	ds_write2_b64 v8, v[204:205], v[206:207] offset1:1
	s_waitcnt vmcnt(4)
	v_add_u32_e32 v8, 0x3300, v126
	ds_write2_b64 v8, v[208:209], v[210:211] offset1:1
	s_waitcnt vmcnt(3)
	v_add_u32_e32 v8, 0x3740, v126
	ds_write2_b64 v8, v[212:213], v[214:215] offset1:1
	s_waitcnt vmcnt(2)
	v_add_u32_e32 v8, 0x3b80, v126
	ds_write2_b64 v8, v[216:217], v[218:219] offset1:1
	s_waitcnt vmcnt(1)
	v_add_u32_e32 v8, 0x3fc0, v126
	ds_write2_b64 v8, v[220:221], v[222:223] offset1:1
	v_cmp_lt_i32_e64 s[74:75], s3, v109
	s_add_i32 s30, s3, 1
	v_cmp_lt_i32_e64 s[78:79], s30, v109
	s_and_saveexec_b64 s[72:73], s[74:75]
	s_cbranch_execz .Lgv_mid_end
	ds_write2st64_b32 v122, v130, v131 offset0:68 offset1:69
	v_add_u32_e32 v56, s84, v120
	v_ashrrev_i32_e32 v57, 31, v56
	v_lshlrev_b64 v[58:59], 9, v[56:57]
	v_lshl_add_u64 v[60:61], v[106:107], 0, v[58:59]
	global_load_dword v89, v[60:61], off sc1
	global_load_dword v108, v[60:61], off offset:256 sc1
	v_lshlrev_b64 v[58:59], 11, v[56:57]
	v_lshl_add_u64 v[58:59], v[110:111], 0, v[58:59]
	global_load_dwordx2 v[142:143], v[58:59], off
	s_and_saveexec_b64 s[38:39], s[78:79]
	s_cbranch_execz .Lgv_mid_noidx
	v_add_u32_e32 v58, s84, v56
	v_ashrrev_i32_e32 v59, 31, v58
	v_lshlrev_b64 v[58:59], 9, v[58:59]
	v_lshl_add_u64 v[58:59], v[104:105], 0, v[58:59]
	global_load_dword v130, v[58:59], off
	global_load_dword v131, v[58:59], off offset:256
.Lgv_mid_noidx:
	s_or_b64 exec, exec, s[38:39]
	v_add_u32_e32 v58, 0xffffe000, v56
	v_lshrrev_b32_e32 v58, 12, v58
	v_add_u32_e32 v58, 1, v58
	v_cmp_lt_i32_e64 s[38:39], s22, v56
	s_nop 1
	v_cndmask_b32_e64 v58, 0, v58, s[38:39]
	v_mad_u64_u32 v[58:59], s[38:39], v58, s23, v[112:113]
	global_load_dwordx4 v[4:7], v[58:59], off
	v_add_u32_e32 v62, 0x4400, v123
	ds_read2_b32 v[8:9], v62 offset0:0 offset1:8
	ds_read2_b32 v[10:11], v62 offset0:16 offset1:24
	ds_read2_b32 v[12:13], v62 offset0:32 offset1:40
	ds_read2_b32 v[14:15], v62 offset0:48 offset1:56
	ds_read2_b32 v[16:17], v62 offset0:64 offset1:72
	ds_read2_b32 v[18:19], v62 offset0:80 offset1:88
	ds_read2_b32 v[20:21], v62 offset0:96 offset1:104
	ds_read2_b32 v[22:23], v62 offset0:112 offset1:120
	s_waitcnt lgkmcnt(7)
	v_ashrrev_i32_e32 v57, 31, v8
	v_mov_b32_e32 v56, v8
	v_lshlrev_b64 v[56:57], 7, v[56:57]
	v_lshl_add_u64 v[24:25], v[114:115], 0, v[56:57]
	global_load_dwordx4 v[144:147], v[24:25], off
	v_ashrrev_i32_e32 v57, 31, v9
	v_mov_b32_e32 v56, v9
	v_lshlrev_b64 v[56:57], 7, v[56:57]
	v_lshl_add_u64 v[26:27], v[114:115], 0, v[56:57]
	global_load_dwordx4 v[148:151], v[26:27], off
	s_waitcnt lgkmcnt(6)
	v_ashrrev_i32_e32 v57, 31, v10
	v_mov_b32_e32 v56, v10
	v_lshlrev_b64 v[56:57], 7, v[56:57]
	v_lshl_add_u64 v[28:29], v[114:115], 0, v[56:57]
	global_load_dwordx4 v[152:155], v[28:29], off
	v_ashrrev_i32_e32 v57, 31, v11
	v_mov_b32_e32 v56, v11
	v_lshlrev_b64 v[56:57], 7, v[56:57]
	v_lshl_add_u64 v[30:31], v[114:115], 0, v[56:57]
	global_load_dwordx4 v[156:159], v[30:31], off
	s_waitcnt lgkmcnt(5)
	v_ashrrev_i32_e32 v57, 31, v12
	v_mov_b32_e32 v56, v12
	v_lshlrev_b64 v[56:57], 7, v[56:57]
	v_lshl_add_u64 v[32:33], v[114:115], 0, v[56:57]
	global_load_dwordx4 v[160:163], v[32:33], off
	v_ashrrev_i32_e32 v57, 31, v13
	v_mov_b32_e32 v56, v13
	v_lshlrev_b64 v[56:57], 7, v[56:57]
	v_lshl_add_u64 v[34:35], v[114:115], 0, v[56:57]
	global_load_dwordx4 v[164:167], v[34:35], off
	s_waitcnt lgkmcnt(4)
	v_ashrrev_i32_e32 v57, 31, v14
	v_mov_b32_e32 v56, v14
	v_lshlrev_b64 v[56:57], 7, v[56:57]
	v_lshl_add_u64 v[36:37], v[114:115], 0, v[56:57]
	global_load_dwordx4 v[168:171], v[36:37], off
	v_ashrrev_i32_e32 v57, 31, v15
	v_mov_b32_e32 v56, v15
	v_lshlrev_b64 v[56:57], 7, v[56:57]
	v_lshl_add_u64 v[38:39], v[114:115], 0, v[56:57]
	global_load_dwordx4 v[172:175], v[38:39], off
	s_waitcnt lgkmcnt(3)
	v_ashrrev_i32_e32 v57, 31, v16
	v_mov_b32_e32 v56, v16
	v_lshlrev_b64 v[56:57], 7, v[56:57]
	v_lshl_add_u64 v[40:41], v[114:115], 0, v[56:57]
	global_load_dwordx4 v[192:195], v[40:41], off
	v_ashrrev_i32_e32 v57, 31, v17
	v_mov_b32_e32 v56, v17
	v_lshlrev_b64 v[56:57], 7, v[56:57]
	v_lshl_add_u64 v[42:43], v[114:115], 0, v[56:57]
	global_load_dwordx4 v[196:199], v[42:43], off
	s_waitcnt lgkmcnt(2)
	v_ashrrev_i32_e32 v57, 31, v18
	v_mov_b32_e32 v56, v18
	v_lshlrev_b64 v[56:57], 7, v[56:57]
	v_lshl_add_u64 v[44:45], v[114:115], 0, v[56:57]
	global_load_dwordx4 v[200:203], v[44:45], off
	v_ashrrev_i32_e32 v57, 31, v19
	v_mov_b32_e32 v56, v19
	v_lshlrev_b64 v[56:57], 7, v[56:57]
	v_lshl_add_u64 v[46:47], v[114:115], 0, v[56:57]
	global_load_dwordx4 v[204:207], v[46:47], off
	s_waitcnt lgkmcnt(1)
	v_ashrrev_i32_e32 v57, 31, v20
	v_mov_b32_e32 v56, v20
	v_lshlrev_b64 v[56:57], 7, v[56:57]
	v_lshl_add_u64 v[48:49], v[114:115], 0, v[56:57]
	global_load_dwordx4 v[208:211], v[48:49], off
	v_ashrrev_i32_e32 v57, 31, v21
	v_mov_b32_e32 v56, v21
	v_lshlrev_b64 v[56:57], 7, v[56:57]
	v_lshl_add_u64 v[50:51], v[114:115], 0, v[56:57]
	global_load_dwordx4 v[212:215], v[50:51], off
	s_waitcnt lgkmcnt(0)
	v_ashrrev_i32_e32 v57, 31, v22
	v_mov_b32_e32 v56, v22
	v_lshlrev_b64 v[56:57], 7, v[56:57]
	v_lshl_add_u64 v[52:53], v[114:115], 0, v[56:57]
	global_load_dwordx4 v[216:219], v[52:53], off
	v_ashrrev_i32_e32 v57, 31, v23
	v_mov_b32_e32 v56, v23
	v_lshlrev_b64 v[56:57], 7, v[56:57]
	v_lshl_add_u64 v[54:55], v[114:115], 0, v[56:57]
	global_load_dwordx4 v[220:223], v[54:55], off
.Lgv_mid_end:
	s_or_b64 exec, exec, s[72:73]
	ds_read_b64_tr_b4 v[68:69], v127
	ds_read_b64_tr_b4 v[64:65], v127 offset:8
	ds_read_b64_tr_b4 v[60:61], v127 offset:16
	ds_read_b64_tr_b4 v[56:57], v127 offset:24
	ds_read_b64_tr_b4 v[52:53], v127 offset:32
	ds_read_b64_tr_b4 v[48:49], v127 offset:40
	ds_read_b64_tr_b4 v[44:45], v127 offset:48
	ds_read_b64_tr_b4 v[36:37], v127 offset:56
	ds_read_b64_tr_b4 v[70:71], v127 offset:2176
	ds_read_b64_tr_b4 v[66:67], v127 offset:2184
	ds_read_b64_tr_b4 v[62:63], v127 offset:2192
	ds_read_b64_tr_b4 v[58:59], v127 offset:2200
	ds_read_b64_tr_b4 v[54:55], v127 offset:2208
	ds_read_b64_tr_b4 v[50:51], v127 offset:2216
	ds_read_b64_tr_b4 v[46:47], v127 offset:2224
	ds_read_b64_tr_b4 v[38:39], v127 offset:2232
	ds_read_b64_tr_b4 v[40:41], v127 offset:64
	ds_read_b64_tr_b4 v[32:33], v127 offset:72
	ds_read_b64_tr_b4 v[28:29], v127 offset:80
	ds_read_b64_tr_b4 v[24:25], v127 offset:88
	ds_read_b64_tr_b4 v[42:43], v127 offset:2240
	ds_read_b64_tr_b4 v[34:35], v127 offset:2248
	ds_read_b64_tr_b4 v[30:31], v127 offset:2256
	ds_read_b64_tr_b4 v[26:27], v127 offset:2264
	ds_read_b64_tr_b4 v[20:21], v127 offset:96
	ds_read_b64_tr_b4 v[16:17], v127 offset:104
	ds_read_b64_tr_b4 v[12:13], v127 offset:112
	ds_read_b64_tr_b4 v[8:9], v127 offset:120
	ds_read_b64_tr_b4 v[22:23], v127 offset:2272
	ds_read_b64_tr_b4 v[18:19], v127 offset:2280
	ds_read_b64_tr_b4 v[14:15], v127 offset:2288
	ds_read_b64_tr_b4 v[10:11], v127 offset:2296
	s_and_saveexec_b64 s[52:53], s[50:51]
	s_cbranch_execz .LBB0_1116
	s_waitcnt lgkmcnt(14)
	v_mfma_scale_f32_16x16x128_f8f6f4 v[138:141], v[84:87], v[68:71], 0, v183, v183 op_sel_hi:[0,0,0] cbsz:4 blgp:4
	v_mfma_scale_f32_16x16x128_f8f6f4 v[138:141], v[80:83], v[68:71], v[138:141], v184, v183 op_sel_hi:[0,0,0] cbsz:4 blgp:4
	v_mfma_scale_f32_16x16x128_f8f6f4 v[138:141], v[76:79], v[68:71], v[138:141], v185, v183 op_sel_hi:[0,0,0] cbsz:4 blgp:4
	v_mfma_scale_f32_16x16x128_f8f6f4 v[68:71], v[72:75], v[68:71], v[138:141], v186, v183 op_sel_hi:[0,0,0] cbsz:4 blgp:4
	v_mfma_scale_f32_16x16x128_f8f6f4 v[138:141], v[84:87], v[64:67], 0, v183, v183 op_sel_hi:[0,0,0] cbsz:4 blgp:4
	v_mfma_scale_f32_16x16x128_f8f6f4 v[138:141], v[80:83], v[64:67], v[138:141], v184, v183 op_sel_hi:[0,0,0] cbsz:4 blgp:4
	v_mfma_scale_f32_16x16x128_f8f6f4 v[138:141], v[76:79], v[64:67], v[138:141], v185, v183 op_sel_hi:[0,0,0] cbsz:4 blgp:4
	v_mfma_scale_f32_16x16x128_f8f6f4 v[64:67], v[72:75], v[64:67], v[138:141], v186, v183 op_sel_hi:[0,0,0] cbsz:4 blgp:4
	v_mfma_scale_f32_16x16x128_f8f6f4 v[138:141], v[84:87], v[60:63], 0, v183, v183 op_sel_hi:[0,0,0] cbsz:4 blgp:4
	v_mfma_scale_f32_16x16x128_f8f6f4 v[138:141], v[80:83], v[60:63], v[138:141], v184, v183 op_sel_hi:[0,0,0] cbsz:4 blgp:4
	s_nop 5
	ds_write2_b32 v122, v68, v64 offset1:16
	v_mfma_scale_f32_16x16x128_f8f6f4 v[138:141], v[76:79], v[60:63], v[138:141], v185, v183 op_sel_hi:[0,0,0] cbsz:4 blgp:4
	v_mfma_scale_f32_16x16x128_f8f6f4 v[60:63], v[72:75], v[60:63], v[138:141], v186, v183 op_sel_hi:[0,0,0] cbsz:4 blgp:4
	v_mfma_scale_f32_16x16x128_f8f6f4 v[138:141], v[84:87], v[56:59], 0, v183, v183 op_sel_hi:[0,0,0] cbsz:4 blgp:4
	v_mfma_scale_f32_16x16x128_f8f6f4 v[138:141], v[80:83], v[56:59], v[138:141], v184, v183 op_sel_hi:[0,0,0] cbsz:4 blgp:4
	v_mfma_scale_f32_16x16x128_f8f6f4 v[138:141], v[76:79], v[56:59], v[138:141], v185, v183 op_sel_hi:[0,0,0] cbsz:4 blgp:4
	v_mfma_scale_f32_16x16x128_f8f6f4 v[56:59], v[72:75], v[56:59], v[138:141], v186, v183 op_sel_hi:[0,0,0] cbsz:4 blgp:4
	v_mfma_scale_f32_16x16x128_f8f6f4 v[138:141], v[84:87], v[52:55], 0, v183, v183 op_sel_hi:[0,0,0] cbsz:4 blgp:4
	v_mfma_scale_f32_16x16x128_f8f6f4 v[138:141], v[80:83], v[52:55], v[138:141], v184, v183 op_sel_hi:[0,0,0] cbsz:4 blgp:4
	v_mfma_scale_f32_16x16x128_f8f6f4 v[138:141], v[76:79], v[52:55], v[138:141], v185, v183 op_sel_hi:[0,0,0] cbsz:4 blgp:4
	v_mfma_scale_f32_16x16x128_f8f6f4 v[52:55], v[72:75], v[52:55], v[138:141], v186, v183 op_sel_hi:[0,0,0] cbsz:4 blgp:4
	v_mfma_scale_f32_16x16x128_f8f6f4 v[138:141], v[84:87], v[48:51], 0, v183, v183 op_sel_hi:[0,0,0] cbsz:4 blgp:4
	v_mfma_scale_f32_16x16x128_f8f6f4 v[138:141], v[80:83], v[48:51], v[138:141], v184, v183 op_sel_hi:[0,0,0] cbsz:4 blgp:4
	v_mfma_scale_f32_16x16x128_f8f6f4 v[138:141], v[76:79], v[48:51], v[138:141], v185, v183 op_sel_hi:[0,0,0] cbsz:4 blgp:4
	v_mfma_scale_f32_16x16x128_f8f6f4 v[48:51], v[72:75], v[48:51], v[138:141], v186, v183 op_sel_hi:[0,0,0] cbsz:4 blgp:4
	v_mfma_scale_f32_16x16x128_f8f6f4 v[138:141], v[84:87], v[44:47], 0, v183, v183 op_sel_hi:[0,0,0] cbsz:4 blgp:4
	v_mfma_scale_f32_16x16x128_f8f6f4 v[138:141], v[80:83], v[44:47], v[138:141], v184, v183 op_sel_hi:[0,0,0] cbsz:4 blgp:4
	v_mfma_scale_f32_16x16x128_f8f6f4 v[138:141], v[76:79], v[44:47], v[138:141], v185, v183 op_sel_hi:[0,0,0] cbsz:4 blgp:4
	v_mfma_scale_f32_16x16x128_f8f6f4 v[44:47], v[72:75], v[44:47], v[138:141], v186, v183 op_sel_hi:[0,0,0] cbsz:4 blgp:4
	v_mfma_scale_f32_16x16x128_f8f6f4 v[138:141], v[84:87], v[36:39], 0, v183, v183 op_sel_hi:[0,0,0] cbsz:4 blgp:4
	v_mfma_scale_f32_16x16x128_f8f6f4 v[138:141], v[80:83], v[36:39], v[138:141], v184, v183 op_sel_hi:[0,0,0] cbsz:4 blgp:4
	v_mfma_scale_f32_16x16x128_f8f6f4 v[138:141], v[76:79], v[36:39], v[138:141], v185, v183 op_sel_hi:[0,0,0] cbsz:4 blgp:4
	v_mfma_scale_f32_16x16x128_f8f6f4 v[36:39], v[72:75], v[36:39], v[138:141], v186, v183 op_sel_hi:[0,0,0] cbsz:4 blgp:4
	ds_write2_b32 v122, v60, v56 offset0:32 offset1:48
	ds_write2_b32 v122, v52, v48 offset0:64 offset1:80
	s_nop 5
	ds_write2_b32 v122, v44, v36 offset0:96 offset1:112
	s_waitcnt lgkmcnt(14)
	v_mfma_scale_f32_16x16x128_f8f6f4 v[138:141], v[84:87], v[40:43], 0, v183, v183 op_sel_hi:[0,0,0] cbsz:4 blgp:4
	v_mfma_scale_f32_16x16x128_f8f6f4 v[138:141], v[80:83], v[40:43], v[138:141], v184, v183 op_sel_hi:[0,0,0] cbsz:4 blgp:4
	v_mfma_scale_f32_16x16x128_f8f6f4 v[138:141], v[76:79], v[40:43], v[138:141], v185, v183 op_sel_hi:[0,0,0] cbsz:4 blgp:4
	v_mfma_scale_f32_16x16x128_f8f6f4 v[38:41], v[72:75], v[40:43], v[138:141], v186, v183 op_sel_hi:[0,0,0] cbsz:4 blgp:4
	v_mfma_scale_f32_16x16x128_f8f6f4 v[40:43], v[84:87], v[32:35], 0, v183, v183 op_sel_hi:[0,0,0] cbsz:4 blgp:4
	v_mfma_scale_f32_16x16x128_f8f6f4 v[40:43], v[80:83], v[32:35], v[40:43], v184, v183 op_sel_hi:[0,0,0] cbsz:4 blgp:4
	v_mfma_scale_f32_16x16x128_f8f6f4 v[40:43], v[76:79], v[32:35], v[40:43], v185, v183 op_sel_hi:[0,0,0] cbsz:4 blgp:4
	v_mfma_scale_f32_16x16x128_f8f6f4 v[32:35], v[72:75], v[32:35], v[40:43], v186, v183 op_sel_hi:[0,0,0] cbsz:4 blgp:4
	s_waitcnt lgkmcnt(13)
	v_mfma_scale_f32_16x16x128_f8f6f4 v[40:43], v[84:87], v[28:31], 0, v183, v183 op_sel_hi:[0,0,0] cbsz:4 blgp:4
	v_mfma_scale_f32_16x16x128_f8f6f4 v[40:43], v[80:83], v[28:31], v[40:43], v184, v183 op_sel_hi:[0,0,0] cbsz:4 blgp:4
	v_mfma_scale_f32_16x16x128_f8f6f4 v[40:43], v[76:79], v[28:31], v[40:43], v185, v183 op_sel_hi:[0,0,0] cbsz:4 blgp:4
	v_mfma_scale_f32_16x16x128_f8f6f4 v[28:31], v[72:75], v[28:31], v[40:43], v186, v183 op_sel_hi:[0,0,0] cbsz:4 blgp:4
	s_waitcnt lgkmcnt(12)
	v_mfma_scale_f32_16x16x128_f8f6f4 v[40:43], v[84:87], v[24:27], 0, v183, v183 op_sel_hi:[0,0,0] cbsz:4 blgp:4
	v_mfma_scale_f32_16x16x128_f8f6f4 v[40:43], v[80:83], v[24:27], v[40:43], v184, v183 op_sel_hi:[0,0,0] cbsz:4 blgp:4
	v_mfma_scale_f32_16x16x128_f8f6f4 v[40:43], v[76:79], v[24:27], v[40:43], v185, v183 op_sel_hi:[0,0,0] cbsz:4 blgp:4
	v_mfma_scale_f32_16x16x128_f8f6f4 v[24:27], v[72:75], v[24:27], v[40:43], v186, v183 op_sel_hi:[0,0,0] cbsz:4 blgp:4
	s_waitcnt lgkmcnt(7)
	v_mfma_scale_f32_16x16x128_f8f6f4 v[40:43], v[84:87], v[20:23], 0, v183, v183 op_sel_hi:[0,0,0] cbsz:4 blgp:4
	v_mfma_scale_f32_16x16x128_f8f6f4 v[40:43], v[80:83], v[20:23], v[40:43], v184, v183 op_sel_hi:[0,0,0] cbsz:4 blgp:4
	v_mfma_scale_f32_16x16x128_f8f6f4 v[40:43], v[76:79], v[20:23], v[40:43], v185, v183 op_sel_hi:[0,0,0] cbsz:4 blgp:4
	v_mfma_scale_f32_16x16x128_f8f6f4 v[20:23], v[72:75], v[20:23], v[40:43], v186, v183 op_sel_hi:[0,0,0] cbsz:4 blgp:4
	s_waitcnt lgkmcnt(6)
	v_mfma_scale_f32_16x16x128_f8f6f4 v[40:43], v[84:87], v[16:19], 0, v183, v183 op_sel_hi:[0,0,0] cbsz:4 blgp:4
	v_mfma_scale_f32_16x16x128_f8f6f4 v[40:43], v[80:83], v[16:19], v[40:43], v184, v183 op_sel_hi:[0,0,0] cbsz:4 blgp:4
	v_mfma_scale_f32_16x16x128_f8f6f4 v[40:43], v[76:79], v[16:19], v[40:43], v185, v183 op_sel_hi:[0,0,0] cbsz:4 blgp:4
	v_mfma_scale_f32_16x16x128_f8f6f4 v[16:19], v[72:75], v[16:19], v[40:43], v186, v183 op_sel_hi:[0,0,0] cbsz:4 blgp:4
	ds_write2_b32 v122, v38, v32 offset0:128 offset1:144
	ds_write2_b32 v122, v28, v24 offset0:160 offset1:176
	s_nop 5
	ds_write2_b32 v122, v20, v16 offset0:192 offset1:208
	s_waitcnt lgkmcnt(8)
	v_mfma_scale_f32_16x16x128_f8f6f4 v[40:43], v[84:87], v[12:15], 0, v183, v183 op_sel_hi:[0,0,0] cbsz:4 blgp:4
	v_mfma_scale_f32_16x16x128_f8f6f4 v[40:43], v[80:83], v[12:15], v[40:43], v184, v183 op_sel_hi:[0,0,0] cbsz:4 blgp:4
	v_mfma_scale_f32_16x16x128_f8f6f4 v[40:43], v[76:79], v[12:15], v[40:43], v185, v183 op_sel_hi:[0,0,0] cbsz:4 blgp:4
	v_mfma_scale_f32_16x16x128_f8f6f4 v[12:15], v[72:75], v[12:15], v[40:43], v186, v183 op_sel_hi:[0,0,0] cbsz:4 blgp:4
	s_waitcnt lgkmcnt(7)
	v_mfma_scale_f32_16x16x128_f8f6f4 v[40:43], v[84:87], v[8:11], 0, v183, v183 op_sel_hi:[0,0,0] cbsz:4 blgp:4
	v_mfma_scale_f32_16x16x128_f8f6f4 v[40:43], v[80:83], v[8:11], v[40:43], v184, v183 op_sel_hi:[0,0,0] cbsz:4 blgp:4
	v_mfma_scale_f32_16x16x128_f8f6f4 v[34:37], v[76:79], v[8:11], v[40:43], v185, v183 op_sel_hi:[0,0,0] cbsz:4 blgp:4
	v_mfma_scale_f32_16x16x128_f8f6f4 v[8:11], v[72:75], v[8:11], v[34:37], v186, v183 op_sel_hi:[0,0,0] cbsz:4 blgp:4
	s_nop 7
	ds_write2_b32 v122, v12, v8 offset0:224 offset1:240
	s_branch .LBB0_1116
